# P0 x-row loop: 8 loads issued up front, counted vmcnt
# baseline (speedup 1.0000x reference)
; __device__ __forceinline__ unsigned pk2(float lo, float hi) { f32x2 v = {lo, hi}; bf16x2_t b = __builtin_convertvector(v, bf16x2_t); return __builtin_bit_cast(unsigned, b); }
; __global__ void __launch_bounds__(NTHR, 2) fwd_kernel(Args args) {
;     ...
;         for (int mrow = gw; mrow < M; mrow += NGW) {
;             const f32x4* xr = (const f32x4*)(P.x + (size_t)mrow * DM) + lane; u32x2* ob = (u32x2*)(P.XB() + (size_t)mrow * DM) + lane; unsigned* o8 = (unsigned*)(P.XB8() + (size_t)mrow * DM) + lane; float s = 0.f;
; #pragma unroll
;             for (int jv = 0; jv < 8; ++jv) { const f32x4 v = xr[64 * jv]; s += (v[0] * v[0] + v[1] * v[1]) + (v[2] * v[2] + v[3] * v[3]); ob[64 * jv] = (u32x2){pk2(v[0], v[1]), pk2(v[2], v[3])};
;                 int q = 0; q = __builtin_amdgcn_cvt_pk_fp8_f32(v[0] * 8.f, v[1] * 8.f, q, false); q = __builtin_amdgcn_cvt_pk_fp8_f32(v[2] * 8.f, v[3] * 8.f, q, true); o8[64 * jv] = (unsigned)q; }
;             s = wave_sum(s);
;             if (lane == 0) P.SSQ()[mrow] = s;
;         }
.LBB0_511:
	s_waitcnt lgkmcnt(0)
	global_load_dwordx4 v[18:21], v[0:1], off offset:-4096
	global_load_dwordx4 v[22:25], v[0:1], off offset:-3072
	global_load_dwordx4 v[26:29], v[0:1], off offset:-2048
	global_load_dwordx4 v[30:33], v[0:1], off offset:-1024
	global_load_dwordx4 v[34:37], v[0:1], off
	global_load_dwordx4 v[38:41], v[0:1], off offset:1024
	global_load_dwordx4 v[42:45], v[0:1], off offset:2048
	global_load_dwordx4 v[46:49], v[0:1], off offset:3072
	v_lshl_add_u64 v[6:7], s[18:19], 0, v[4:5]
	v_add_co_u32_e32 v6, vcc, s14, v6
	v_lshl_add_u64 v[8:9], s[18:19], 0, v[2:3]
	s_nop 0
	v_addc_co_u32_e32 v7, vcc, 0, v7, vcc
	v_add_co_u32_e32 v8, vcc, s15, v8
	s_nop 1
	v_addc_co_u32_e32 v9, vcc, 0, v9, vcc
	s_waitcnt vmcnt(7)
	v_mul_f32_e32 v160, 0x41000000, v18
	v_mul_f32_e32 v161, 0x41000000, v19
	v_cvt_pk_fp8_f32 v170, v160, v161
	v_mul_f32_e32 v160, 0x41000000, v20
	v_mul_f32_e32 v161, 0x41000000, v21
	v_cvt_pk_fp8_f32 v170, v160, v161 op_sel:[0,0,1]
	v_cvt_pk_bf16_f32 v180, v18, v19
	v_cvt_pk_bf16_f32 v181, v20, v21
	v_mul_f32_e32 v163, v19, v19
	v_mul_f32_e32 v164, v21, v21
	v_fmac_f32_e32 v163, v18, v18
	v_fmac_f32_e32 v164, v20, v20
	global_store_dwordx2 v[6:7], v[180:181], off
	global_store_dword v[8:9], v170, off
	v_add_f32_e32 v162, v163, v164
	s_waitcnt vmcnt(8)
	v_mul_f32_e32 v160, 0x41000000, v22
	v_mul_f32_e32 v161, 0x41000000, v23
	v_cvt_pk_fp8_f32 v171, v160, v161
	v_mul_f32_e32 v160, 0x41000000, v24
	v_mul_f32_e32 v161, 0x41000000, v25
	v_cvt_pk_fp8_f32 v171, v160, v161 op_sel:[0,0,1]
	v_cvt_pk_bf16_f32 v182, v22, v23
	v_cvt_pk_bf16_f32 v183, v24, v25
	v_mul_f32_e32 v163, v23, v23
	v_mul_f32_e32 v164, v25, v25
	v_fmac_f32_e32 v163, v22, v22
	v_fmac_f32_e32 v164, v24, v24
	global_store_dwordx2 v[6:7], v[182:183], off offset:512
	global_store_dword v[8:9], v171, off offset:256
	v_add_f32_e32 v163, v163, v164
	v_add_f32_e32 v162, v162, v163
	s_waitcnt vmcnt(9)
	v_mul_f32_e32 v160, 0x41000000, v26
	v_mul_f32_e32 v161, 0x41000000, v27
	v_cvt_pk_fp8_f32 v172, v160, v161
	v_mul_f32_e32 v160, 0x41000000, v28
	v_mul_f32_e32 v161, 0x41000000, v29
	v_cvt_pk_fp8_f32 v172, v160, v161 op_sel:[0,0,1]
	v_cvt_pk_bf16_f32 v184, v26, v27
	v_cvt_pk_bf16_f32 v185, v28, v29
	v_mul_f32_e32 v163, v27, v27
	v_mul_f32_e32 v164, v29, v29
	v_fmac_f32_e32 v163, v26, v26
	v_fmac_f32_e32 v164, v28, v28
	global_store_dwordx2 v[6:7], v[184:185], off offset:1024
	global_store_dword v[8:9], v172, off offset:512
	v_add_f32_e32 v163, v163, v164
	v_add_f32_e32 v162, v162, v163
	s_waitcnt vmcnt(10)
	v_mul_f32_e32 v160, 0x41000000, v30
	v_mul_f32_e32 v161, 0x41000000, v31
	v_cvt_pk_fp8_f32 v173, v160, v161
	v_mul_f32_e32 v160, 0x41000000, v32
	v_mul_f32_e32 v161, 0x41000000, v33
	v_cvt_pk_fp8_f32 v173, v160, v161 op_sel:[0,0,1]
	v_cvt_pk_bf16_f32 v186, v30, v31
	v_cvt_pk_bf16_f32 v187, v32, v33
	v_mul_f32_e32 v163, v31, v31
	v_mul_f32_e32 v164, v33, v33
	v_fmac_f32_e32 v163, v30, v30
	v_fmac_f32_e32 v164, v32, v32
	global_store_dwordx2 v[6:7], v[186:187], off offset:1536
	global_store_dword v[8:9], v173, off offset:768
	v_add_f32_e32 v163, v163, v164
	v_add_f32_e32 v162, v162, v163
	s_waitcnt vmcnt(11)
	v_mul_f32_e32 v160, 0x41000000, v34
	v_mul_f32_e32 v161, 0x41000000, v35
	v_cvt_pk_fp8_f32 v174, v160, v161
	v_mul_f32_e32 v160, 0x41000000, v36
	v_mul_f32_e32 v161, 0x41000000, v37
	v_cvt_pk_fp8_f32 v174, v160, v161 op_sel:[0,0,1]
	v_cvt_pk_bf16_f32 v188, v34, v35
	v_cvt_pk_bf16_f32 v189, v36, v37
	v_mul_f32_e32 v163, v35, v35
	v_mul_f32_e32 v164, v37, v37
	v_fmac_f32_e32 v163, v34, v34
	v_fmac_f32_e32 v164, v36, v36
	global_store_dwordx2 v[6:7], v[188:189], off offset:2048
	global_store_dword v[8:9], v174, off offset:1024
	v_add_f32_e32 v163, v163, v164
	v_add_f32_e32 v162, v162, v163
	s_waitcnt vmcnt(12)
	v_mul_f32_e32 v160, 0x41000000, v38
	v_mul_f32_e32 v161, 0x41000000, v39
	v_cvt_pk_fp8_f32 v175, v160, v161
	v_mul_f32_e32 v160, 0x41000000, v40
	v_mul_f32_e32 v161, 0x41000000, v41
	v_cvt_pk_fp8_f32 v175, v160, v161 op_sel:[0,0,1]
	v_cvt_pk_bf16_f32 v190, v38, v39
	v_cvt_pk_bf16_f32 v191, v40, v41
	v_mul_f32_e32 v163, v39, v39
	v_mul_f32_e32 v164, v41, v41
	v_fmac_f32_e32 v163, v38, v38
	v_fmac_f32_e32 v164, v40, v40
	global_store_dwordx2 v[6:7], v[190:191], off offset:2560
	global_store_dword v[8:9], v175, off offset:1280
	v_add_f32_e32 v163, v163, v164
	v_add_f32_e32 v162, v162, v163
	s_waitcnt vmcnt(13)
	v_mul_f32_e32 v160, 0x41000000, v42
	v_mul_f32_e32 v161, 0x41000000, v43
	v_cvt_pk_fp8_f32 v176, v160, v161
	v_mul_f32_e32 v160, 0x41000000, v44
	v_mul_f32_e32 v161, 0x41000000, v45
	v_cvt_pk_fp8_f32 v176, v160, v161 op_sel:[0,0,1]
	v_cvt_pk_bf16_f32 v192, v42, v43
	v_cvt_pk_bf16_f32 v193, v44, v45
	v_mul_f32_e32 v163, v43, v43
	v_mul_f32_e32 v164, v45, v45
	v_fmac_f32_e32 v163, v42, v42
	v_fmac_f32_e32 v164, v44, v44
	global_store_dwordx2 v[6:7], v[192:193], off offset:3072
	global_store_dword v[8:9], v176, off offset:1536
	v_add_f32_e32 v163, v163, v164
	v_add_f32_e32 v162, v162, v163
	s_waitcnt vmcnt(14)
	v_mul_f32_e32 v160, 0x41000000, v46
	v_mul_f32_e32 v161, 0x41000000, v47
	v_cvt_pk_fp8_f32 v177, v160, v161
	v_mul_f32_e32 v160, 0x41000000, v48
	v_mul_f32_e32 v161, 0x41000000, v49
	v_cvt_pk_fp8_f32 v177, v160, v161 op_sel:[0,0,1]
	v_cvt_pk_bf16_f32 v194, v46, v47
	v_cvt_pk_bf16_f32 v195, v48, v49
	v_mul_f32_e32 v163, v47, v47
	v_mul_f32_e32 v164, v49, v49
	v_fmac_f32_e32 v163, v46, v46
	v_fmac_f32_e32 v164, v48, v48
	global_store_dwordx2 v[6:7], v[194:195], off offset:3584
	global_store_dword v[8:9], v177, off offset:1792
	v_add_f32_e32 v163, v163, v164
	v_add_f32_e32 v162, v162, v163
	ds_bpermute_b32 v163, v10, v162
	s_waitcnt lgkmcnt(0)
	v_add_f32_e32 v162, v162, v163
	ds_bpermute_b32 v163, v11, v162
	s_waitcnt lgkmcnt(0)
	v_add_f32_e32 v162, v162, v163
	ds_bpermute_b32 v163, v12, v162
	s_waitcnt lgkmcnt(0)
	v_add_f32_e32 v162, v162, v163
	ds_bpermute_b32 v163, v13, v162
	s_waitcnt lgkmcnt(0)
	v_add_f32_e32 v162, v162, v163
	ds_bpermute_b32 v163, v14, v162
	s_waitcnt lgkmcnt(0)
	v_add_f32_e32 v162, v162, v163
	ds_bpermute_b32 v163, v15, v162
	s_and_saveexec_b64 s[10:11], s[2:3]
	s_cbranch_execz .LBB0_510
	s_add_u32 s16, s18, s12
	s_addc_u32 s17, s19, s13
	s_waitcnt lgkmcnt(0)
	v_add_f32_e32 v6, v162, v163
	global_store_dword v17, v6, s[16:17]
	s_branch .LBB0_510
